# also no cache invalidate at the barriers after P3 and P4 (one invalidate per layer remains, after P1): within a layer every buffer is written once before any other CU loads it
# speedup vs baseline: 1.0344x; 1.0069x over previous
.LBB0_889:
	s_or_b64 exec, exec, s[14:15]
	s_waitcnt vmcnt(0) lgkmcnt(0)
	s_nop 0
	s_waitcnt vmcnt(0)
.LBB0_890:
	s_andn2_saveexec_b64 s[8:9], s[12:13]
	s_cbranch_execz .LBB0_906
	s_add_i32 s101, s101, 1
	v_mov_b32_e32 v1, s54
	v_add_co_u32_e32 v2, vcc, 0x3000, v1
	v_mov_b32_e32 v1, s55
	buffer_wbl2 sc1
	s_waitcnt vmcnt(0)
	v_addc_co_u32_e32 v3, vcc, 0, v1, vcc
	flat_atomic_add v1, v[2:3], v228 offset:1024 sc0
	v_cvt_f32_u32_e32 v2, v0
	v_sub_u32_e32 v3, 0, v0
	s_add_u32 s12, s54, 0x3400
	s_addc_u32 s13, s55, 0
	v_rcp_iflag_f32_e32 v2, v2
	s_mov_b64 s[16:17], -1
	v_mul_f32_e32 v2, 0x4f7ffffe, v2
	v_cvt_u32_f32_e32 v2, v2
	v_mul_lo_u32 v3, v3, v2
	v_mul_hi_u32 v3, v2, v3
	v_add_u32_e32 v2, v2, v3
	s_waitcnt vmcnt(0) lgkmcnt(0)
	v_mul_hi_u32 v2, v1, v2
	v_mul_lo_u32 v3, v2, v0
	v_sub_u32_e32 v3, v1, v3
	v_cmp_ge_u32_e32 vcc, v3, v0
	v_add_u32_e32 v4, 1, v2
	s_nop 0
	v_cndmask_b32_e32 v2, v2, v4, vcc
	v_sub_u32_e32 v4, v3, v0
	v_cndmask_b32_e32 v3, v3, v4, vcc
	v_cmp_ge_u32_e32 vcc, v3, v0
	v_add_u32_e32 v3, 1, v2
	s_nop 0
	v_cndmask_b32_e32 v2, v2, v3, vcc
	v_add_u32_e32 v3, 1, v1
	v_mad_u64_u32 v[0:1], s[8:9], v0, v2, v[0:1]
	v_cmp_ne_u32_e32 vcc, v3, v0
	v_mov_b32_e32 v3, v0
	v_mov_b64_e32 v[0:1], s[12:13]
	s_and_saveexec_b64 s[14:15], vcc
	s_cbranch_execz .LBB0_903
	v_mov_b64_e32 v[0:1], s[12:13]
	flat_load_dword v0, v[0:1] sc1
	s_mov_b64 s[20:21], 0
	s_waitcnt vmcnt(0) lgkmcnt(0)
	v_cmp_lt_u32_e32 vcc, v0, v3
	s_and_saveexec_b64 s[18:19], vcc
	s_cbranch_execz .LBB0_902
	s_add_u32 s16, s54, 0x200
	s_addc_u32 s17, s55, 0
	s_mov_b32 s7, 1
	s_branch .LBB0_895

.LBB0_905:
	s_or_b64 exec, exec, s[12:13]
	s_add_i32 s82, s6, 0x900
	s_lshl_b64 s[6:7], s[82:83], 2
	s_add_u32 s6, s54, s6
	s_addc_u32 s7, s55, s7
	v_mov_b64_e32 v[0:1], s[6:7]
	s_waitcnt vmcnt(0) lgkmcnt(0)
	s_nop 0
	flat_atomic_add v[0:1], v228
	s_waitcnt vmcnt(0)

.LBB0_1133:
	s_or_b64 exec, exec, s[18:19]
	s_xor_b64 s[8:9], s[20:21], -1
	s_and_saveexec_b64 s[16:17], s[8:9]
	s_xor_b64 s[16:17], exec, s[16:17]
	s_cbranch_execz .LBB0_1135
	v_mov_b64_e32 v[0:1], s[50:51]
	flat_atomic_add v[0:1], v228 offset:512
.LBB0_1135:
	s_or_b64 exec, exec, s[14:15]
	s_waitcnt vmcnt(0) lgkmcnt(0)
	s_nop 0
	s_waitcnt vmcnt(0)
.LBB0_1136:
	s_andn2_saveexec_b64 s[8:9], s[12:13]
	s_cbranch_execz .LBB0_1152
	s_add_i32 s101, s101, 1
	v_mov_b32_e32 v1, s50
	v_add_co_u32_e32 v2, vcc, 0x3000, v1
	v_mov_b32_e32 v1, s51
	buffer_wbl2 sc1
	s_waitcnt vmcnt(0)
	v_addc_co_u32_e32 v3, vcc, 0, v1, vcc
	flat_atomic_add v1, v[2:3], v228 offset:1024 sc0
	v_cvt_f32_u32_e32 v2, v0
	v_sub_u32_e32 v3, 0, v0
	s_add_u32 s12, s50, 0x3400
	s_addc_u32 s13, s51, 0
	v_rcp_iflag_f32_e32 v2, v2
	s_mov_b64 s[16:17], -1
	v_mul_f32_e32 v2, 0x4f7ffffe, v2
	v_cvt_u32_f32_e32 v2, v2
	v_mul_lo_u32 v3, v3, v2
	v_mul_hi_u32 v3, v2, v3
	v_add_u32_e32 v2, v2, v3
	s_waitcnt vmcnt(0) lgkmcnt(0)
	v_mul_hi_u32 v2, v1, v2
	v_mul_lo_u32 v3, v2, v0
	v_sub_u32_e32 v3, v1, v3
	v_cmp_ge_u32_e32 vcc, v3, v0
	v_add_u32_e32 v4, 1, v2
	s_nop 0
	v_cndmask_b32_e32 v2, v2, v4, vcc
	v_sub_u32_e32 v4, v3, v0
	v_cndmask_b32_e32 v3, v3, v4, vcc
	v_cmp_ge_u32_e32 vcc, v3, v0
	v_add_u32_e32 v3, 1, v2
	s_nop 0
	v_cndmask_b32_e32 v2, v2, v3, vcc
	v_add_u32_e32 v3, 1, v1
	v_mad_u64_u32 v[0:1], s[8:9], v0, v2, v[0:1]
	v_cmp_ne_u32_e32 vcc, v3, v0
	v_mov_b32_e32 v3, v0
	v_mov_b64_e32 v[0:1], s[12:13]
	s_and_saveexec_b64 s[14:15], vcc
	s_cbranch_execz .LBB0_1149
	v_mov_b64_e32 v[0:1], s[12:13]
	flat_load_dword v0, v[0:1] sc1
	s_mov_b64 s[20:21], 0
	s_waitcnt vmcnt(0) lgkmcnt(0)
	v_cmp_lt_u32_e32 vcc, v0, v3
	s_and_saveexec_b64 s[18:19], vcc
	s_cbranch_execz .LBB0_1148
	s_add_u32 s16, s50, 0x200
	s_addc_u32 s17, s51, 0
	s_mov_b32 s7, 1
	s_branch .LBB0_1141

.LBB0_1151:
	s_or_b64 exec, exec, s[12:13]
	s_add_i32 s82, s6, 0x900
	s_lshl_b64 s[6:7], s[82:83], 2
	s_add_u32 s6, s50, s6
	s_addc_u32 s7, s51, s7
	v_mov_b64_e32 v[0:1], s[6:7]
	s_waitcnt vmcnt(0) lgkmcnt(0)
	s_nop 0
	flat_atomic_add v[0:1], v228
	s_waitcnt vmcnt(0)
